# baseline (speedup 1.0000x reference)
; #define X make_ctx(lds_raw)
; __device__ __forceinline__ void phase0(const Ctx& X, KArgs a) {
;     ...
;     { f32x2* rope = (f32x2*)(ws + WS_ROPE);
;       for (int idx = X.gtid; idx < NT * 32; idx += X.nthr) { const int t = idx >> 5, i = idx & 31;
;           const double rev = (double)a->positions[t] * INVF_REV[i]; const float fr = (float)(rev - floor(rev));
;           rope[idx] = (f32x2){__builtin_amdgcn_cosf(fr), __builtin_amdgcn_sinf(fr)}; } }
.LBB0_16:
	s_mov_b32 s4, 0x80000
	v_cmp_gt_i32_e32 vcc, s4, v2
	s_and_saveexec_b64 s[4:5], vcc
	s_mov_b32 s24, s88
	s_cbranch_execz .LBB0_19
	v_lshlrev_b32_e32 v1, 3, v1
	s_getpc_b64 s[8:9]
	s_add_u32 s8, s8, _ZL8INVF_REV@rel32@lo+4
	s_addc_u32 s9, s9, _ZL8INVF_REV@rel32@hi+12
	global_load_dwordx2 v[4:5], v1, s[8:9]
	s_load_dwordx2 s[6:7], s[6:7], 0x10
	v_ashrrev_i32_e32 v3, 31, v2
	v_lshl_add_u64 v[6:7], v[2:3], 3, s[2:3]
	s_mov_b64 s[2:3], 0x600000
	s_ashr_i32 s25, s24, 31
	v_lshl_add_u64 v[6:7], v[6:7], 0, s[2:3]
	s_lshl_b64 s[2:3], s[24:25], 3
	s_mov_b64 s[8:9], 0
	s_mov_b32 s10, 0x7ffff
	s_waitcnt lgkmcnt(0)
	v_mov_b32_e32 v45, 0
	v_mov_b32_e32 v46, v2
	v_ashrrev_i32_e32 v44, 5, v46
	v_min_i32_e32 v44, 0x3fff, v44
	v_lshl_add_u64 v[48:49], v[44:45], 2, s[6:7]
	global_load_dword v40, v[48:49], off
	v_add_u32_e32 v46, s24, v46
	v_ashrrev_i32_e32 v44, 5, v46
	v_min_i32_e32 v44, 0x3fff, v44
	v_lshl_add_u64 v[48:49], v[44:45], 2, s[6:7]
	global_load_dword v41, v[48:49], off
	v_add_u32_e32 v46, s24, v46
	v_ashrrev_i32_e32 v44, 5, v46
	v_min_i32_e32 v44, 0x3fff, v44
	v_lshl_add_u64 v[48:49], v[44:45], 2, s[6:7]
	global_load_dword v42, v[48:49], off
	v_add_u32_e32 v46, s24, v46
	v_ashrrev_i32_e32 v44, 5, v46
	v_min_i32_e32 v44, 0x3fff, v44
	v_lshl_add_u64 v[48:49], v[44:45], 2, s[6:7]
	global_load_dword v43, v[48:49], off
	v_add_u32_e32 v46, s24, v46
.LBB0_18:
	v_add_u32_e32 v2, s24, v2
	v_cmp_lt_i32_e32 vcc, s10, v2
	s_or_b64 s[8:9], vcc, s[8:9]
	s_waitcnt vmcnt(3)
	v_cvt_f64_i32_e32 v[8:9], v40
	v_mul_f64 v[10:11], v[4:5], v[8:9]
	v_floor_f64_e32 v[10:11], v[10:11]
	v_fma_f64 v[8:9], v[4:5], v[8:9], -v[10:11]
	v_cvt_f32_f64_e32 v1, v[8:9]
	v_cos_f32_e32 v8, v1
	v_sin_f32_e32 v9, v1
	global_store_dwordx2 v[6:7], v[8:9], off
	v_lshl_add_u64 v[6:7], v[6:7], 0, s[2:3]
	s_andn2_b64 exec, exec, s[8:9]
	s_cbranch_execz .LBB0_19
	v_ashrrev_i32_e32 v44, 5, v46
	v_min_i32_e32 v44, 0x3fff, v44
	v_lshl_add_u64 v[48:49], v[44:45], 2, s[6:7]
	global_load_dword v40, v[48:49], off
	v_add_u32_e32 v46, s24, v46
	v_add_u32_e32 v2, s24, v2
	v_cmp_lt_i32_e32 vcc, s10, v2
	s_or_b64 s[8:9], vcc, s[8:9]
	s_waitcnt vmcnt(4)
	v_cvt_f64_i32_e32 v[8:9], v41
	v_mul_f64 v[10:11], v[4:5], v[8:9]
	v_floor_f64_e32 v[10:11], v[10:11]
	v_fma_f64 v[8:9], v[4:5], v[8:9], -v[10:11]
	v_cvt_f32_f64_e32 v1, v[8:9]
	v_cos_f32_e32 v8, v1
	v_sin_f32_e32 v9, v1
	global_store_dwordx2 v[6:7], v[8:9], off
	v_lshl_add_u64 v[6:7], v[6:7], 0, s[2:3]
	s_andn2_b64 exec, exec, s[8:9]
	s_cbranch_execz .LBB0_19
	v_ashrrev_i32_e32 v44, 5, v46
	v_min_i32_e32 v44, 0x3fff, v44
	v_lshl_add_u64 v[48:49], v[44:45], 2, s[6:7]
	global_load_dword v41, v[48:49], off
	v_add_u32_e32 v46, s24, v46
	v_add_u32_e32 v2, s24, v2
	v_cmp_lt_i32_e32 vcc, s10, v2
	s_or_b64 s[8:9], vcc, s[8:9]
	s_waitcnt vmcnt(5)
	v_cvt_f64_i32_e32 v[8:9], v42
	v_mul_f64 v[10:11], v[4:5], v[8:9]
	v_floor_f64_e32 v[10:11], v[10:11]
	v_fma_f64 v[8:9], v[4:5], v[8:9], -v[10:11]
	v_cvt_f32_f64_e32 v1, v[8:9]
	v_cos_f32_e32 v8, v1
	v_sin_f32_e32 v9, v1
	global_store_dwordx2 v[6:7], v[8:9], off
	v_lshl_add_u64 v[6:7], v[6:7], 0, s[2:3]
	s_andn2_b64 exec, exec, s[8:9]
	s_cbranch_execz .LBB0_19
	v_ashrrev_i32_e32 v44, 5, v46
	v_min_i32_e32 v44, 0x3fff, v44
	v_lshl_add_u64 v[48:49], v[44:45], 2, s[6:7]
	global_load_dword v42, v[48:49], off
	v_add_u32_e32 v46, s24, v46
	v_add_u32_e32 v2, s24, v2
	v_cmp_lt_i32_e32 vcc, s10, v2
	s_or_b64 s[8:9], vcc, s[8:9]
	s_waitcnt vmcnt(6)
	v_cvt_f64_i32_e32 v[8:9], v43
	v_mul_f64 v[10:11], v[4:5], v[8:9]
	v_floor_f64_e32 v[10:11], v[10:11]
	v_fma_f64 v[8:9], v[4:5], v[8:9], -v[10:11]
	v_cvt_f32_f64_e32 v1, v[8:9]
	v_cos_f32_e32 v8, v1
	v_sin_f32_e32 v9, v1
	global_store_dwordx2 v[6:7], v[8:9], off
	v_lshl_add_u64 v[6:7], v[6:7], 0, s[2:3]
	s_andn2_b64 exec, exec, s[8:9]
	s_cbranch_execz .LBB0_19
	v_ashrrev_i32_e32 v44, 5, v46
	v_min_i32_e32 v44, 0x3fff, v44
	v_lshl_add_u64 v[48:49], v[44:45], 2, s[6:7]
	global_load_dword v43, v[48:49], off
	v_add_u32_e32 v46, s24, v46
	s_branch .LBB0_18
